# SSD: dt/scan wave chosen per direction (wave 0 fwd, wave 6 bwd) so the scan overlaps other waves' MFMA blocks
# speedup vs baseline: 1.0021x; 1.0021x over previous
; #define LAS __attribute__((address_space(3)))
; __device__ __forceinline__ int opaque_tid() { int t = threadIdx.x; asm volatile("" : "+v"(t)); return t; }
; __device__ __forceinline__ void seq_of(int sq, int& start, int& len) { if (sq < 4) { start = sq * 2048; len = 2048; } else { start = TP + (sq - 4) * 4096; len = 4096; } }
; __device__ __forceinline__ void ssd_item(CP& P, int L, int sq, int hd, int dir, LAS unsigned char* lds) {
;     const int tid = opaque_tid(), lane = tid & 63, wid = __builtin_amdgcn_readfirstlane(tid >> 6), r = lane & 31, hi = lane >> 5;
;     int sstart, slen; seq_of(sq, sstart, slen); const int nc = slen / 128, g = hd / 6;
;     const bf16_t* xbc = (const bf16_t*)(P.ws + WS_XBC); const float* DT = (const float*)(P.ws + WS_DT);
;     bf16_t* Y = (bf16_t*)(P.ws + (dir ? WS_YB : WS_YF));
;     const float Aneg = -__expf(P.in[I_ALOG][L * 24 + dir * 12 + hd]), dtb = P.in[I_DTB][L * 24 + dir * 12 + hd]; const int dcol = dir * 12 + hd;
;     LAS float* AS = (LAS float*)(lds + S_AS); LAS float* DTV = (LAS float*)(lds + S_DTV);
;     f32x16 st;
; #pragma unroll
;     for (int i = 0; i < 16; ++i) st[i] = 0.f;
;     for (int i = tid; i < 64 * SP / 4; i += 512) ((LAS unsigned*)(lds + S_PV))[i] = 0u;
;     const int crow_ = tid >> 4, cch = tid & 15;
;     const int xrow_ = tid >> 3, xch = tid & 7;
;     const int lb = wid >> 1, pb = wid & 1, nb = wid >> 1;
;     const int trq = (lane & 15) >> 2, trb = ((lane >> 4) & 1) * 32 + (lane & 3) * 8;
;     const int xdo = S_XD + (8 * hi + trq) * SXP + 64 * pb + trb;
;     const int bdo = S_BD + (8 * hi + trq) * SP + 64 * nb + trb;
;     u32x4 cv[4], bv[4], xv[2]; float r0 = 0.f, r1 = 0.f;
;     ...
;     SSD_LOAD(sstart + (dir ? nc - 1 : 0) * 128);
.LBB0_89:
	s_or_b64 exec, exec, s[4:5]
	s_bfe_i32 s6, s9, 0x80000
	s_mul_i32 s6, s6, 43
	s_bfe_u32 s7, s6, 0x1000f
	s_bfe_u32 s6, s6, 0x80008
	s_lshl_b32 s4, s2, 12
	s_add_i32 s6, s6, s7
	s_add_i32 s7, s8, 11
	s_addk_i32 s4, 0xe000
	s_lshl_b32 s5, s2, 11
	s_and_b32 s7, s7, 0xff
	s_cmp_lt_i32 s2, 4
	s_cselect_b32 s2, 16, 32
	s_cselect_b32 s9, s5, s4
	s_add_i32 s22, s2, -1
	s_lshl_b32 s8, s22, 7
	s_cmp_lt_u32 s7, 23
	s_cselect_b64 s[40:41], -1, 0
	s_and_b64 s[4:5], s[40:41], exec
	s_cselect_b32 s15, 0, s8
	s_add_i32 s15, s15, s9
	s_mul_i32 s4, s15, 0xa00
	v_readlane_b32 s7, v253, 62
	s_sext_i32_i8 s6, s6
	s_mul_hi_i32 s5, s15, 0xa00
	s_add_u32 s4, s7, s4
	v_readlane_b32 s7, v253, 63
	s_addc_u32 s5, s7, s5
	s_lshl_b32 s6, s6, 7
	v_ashrrev_i32_e32 v15, 4, v5
	s_ashr_i32 s7, s6, 31
	v_mov_b64_e32 v[2:3], s[4:5]
	v_and_b32_e32 v1, 15, v5
	v_writelane_b32 v254, s9, 10
	v_mad_i64_i32 v[8:9], s[8:9], v15, s44, v[2:3]
	s_lshl_b64 s[6:7], s[6:7], 1
	v_lshl_add_u64 v[8:9], v[8:9], 0, s[6:7]
	v_lshlrev_b32_e32 v192, 4, v1
	v_lshl_add_u64 v[8:9], v[8:9], 0, v[192:193]
	v_add_u32_e32 v17, 32, v15
	global_load_dwordx4 v[48:51], v[8:9], off offset:2048
	global_load_dwordx4 v[52:55], v[8:9], off offset:1536
	v_mad_i64_i32 v[8:9], s[8:9], v17, s44, v[2:3]
	v_lshl_add_u64 v[8:9], v[8:9], 0, s[6:7]
	v_lshl_add_u64 v[8:9], v[8:9], 0, v[192:193]
	v_add_u32_e32 v20, 64, v15
	v_add_u32_e32 v21, 0x60, v15
	global_load_dwordx4 v[56:59], v[8:9], off offset:2048
	global_load_dwordx4 v[60:63], v[8:9], off offset:1536
	v_mad_i64_i32 v[8:9], s[8:9], v20, s44, v[2:3]
	v_mad_i64_i32 v[2:3], s[8:9], v21, s44, v[2:3]
	s_lshl_b32 s8, s1, 6
	s_ashr_i32 s9, s8, 31
	v_lshl_add_u64 v[8:9], v[8:9], 0, s[6:7]
	v_lshl_add_u64 v[2:3], v[2:3], 0, s[6:7]
	s_lshl_b64 s[8:9], s[8:9], 1
	v_lshl_add_u64 v[8:9], v[8:9], 0, v[192:193]
	v_lshl_add_u64 v[2:3], v[2:3], 0, v[192:193]
	v_and_b32_e32 v7, 7, v5
	s_add_u32 s4, s4, s8
	global_load_dwordx4 v[64:67], v[8:9], off offset:2048
	global_load_dwordx4 v[68:71], v[8:9], off offset:1536
	global_load_dwordx4 v[72:75], v[2:3], off offset:2048
	global_load_dwordx4 v[76:79], v[2:3], off offset:1536
	s_addc_u32 s5, s5, s9
	v_lshlrev_b32_e32 v2, 4, v7
	v_mov_b32_e32 v3, v193
	v_ashrrev_i32_e32 v16, 3, v5
	v_lshl_add_u64 v[2:3], s[4:5], 0, v[2:3]
	v_mad_i64_i32 v[8:9], s[4:5], v16, s44, v[2:3]
	v_add_u32_e32 v22, 64, v16
	v_mad_i64_i32 v[2:3], s[4:5], v22, s44, v[2:3]
	global_load_dwordx4 v[80:83], v[8:9], off
	global_load_dwordx4 v[84:87], v[2:3], off
	s_and_b64 s[4:5], s[40:41], exec
	s_cselect_b32 s10, 0, 0x180
	s_cmp_eq_u32 s14, s10
	s_cselect_b64 s[10:11], -1, 0
	s_mov_b64 s[4:5], -1
	s_and_b64 vcc, exec, s[10:11]
	s_cbranch_vccnz .LBB0_91
	s_ashr_i32 s1, s0, 31
	s_mov_b64 s[4:5], 0
